# StaticOrder::next group-size division replaced by shift in all 14 GEMM unit loops
# baseline (speedup 1.0000x reference)
;     __host__ __device__ bool next(int i, Unit& u) const {
;         const long L = (long)i * G + c; if (L >= nwg) return false;
;         int wgid = (int)L; { const int q = nwg / NXCD, r = nwg % NXCD, xcd = wgid % NXCD, off = wgid / NXCD; wgid = (xcd < r ? xcd * (q + 1) : r * (q + 1) + (xcd - r) * q) + off; }
;         const int nig = WGM * nN, gid = wgid / nig, fm = gid * WGM, gsz = (nM - fm) < WGM ? (nM - fm) : WGM;
;         u.pm = fm + ((wgid % nig) % gsz); u.pn = (wgid % nig) / gsz; return true;
.LBB0_221:
	s_add_i32 s60, s60, 1
	s_mul_i32 s4, s60, s48
	s_mul_hi_u32 s5, s60, s49
	s_add_i32 s5, s5, s4
	s_mul_i32 s4, s60, s49
	s_add_u32 s16, s4, s2
	s_addc_u32 s17, s5, s3
	v_cmp_gt_i64_e32 vcc, s[16:17], v[142:143]
	v_cmp_lt_i64_e64 s[4:5], s[16:17], v[140:141]
	s_cbranch_vccnz .LBB0_223
	s_ashr_i32 s12, s16, 31
	s_lshr_b32 s12, s12, 29
	s_add_i32 s12, s16, s12
	s_ashr_i32 s13, s12, 3
	s_and_b32 s12, s12, -8
	s_sub_i32 s12, s16, s12
	s_cmp_lt_i32 s12, 0
	s_cselect_b32 s14, s56, 0x160
	s_mul_i32 s12, s14, s12
	s_add_i32 s12, s12, s13
	s_mul_hi_i32 s13, s12, 0x2e8ba2e9
	s_lshr_b32 s14, s13, 31
	s_ashr_i32 s13, s13, 5
	s_add_i32 s13, s13, s14
	s_lshl_b32 s14, s13, 3
	s_sub_i32 s15, 0x80, s14
	s_min_i32 s15, s15, 8
	s_mulk_i32 s13, 0xb0
	s_sub_i32 s13, s12, s13
	s_lshr_b32 s12, s13, 3
	s_mul_i32 s15, s12, s15
	s_sub_i32 s13, s13, s15
	s_add_i32 s14, s13, s14

;     __host__ __device__ bool next(int i, Unit& u) const {
;         const long L = (long)i * G + c; if (L >= nwg) return false;
;         int wgid = (int)L; { const int q = nwg / NXCD, r = nwg % NXCD, xcd = wgid % NXCD, off = wgid / NXCD; wgid = (xcd < r ? xcd * (q + 1) : r * (q + 1) + (xcd - r) * q) + off; }
;         const int nig = WGM * nN, gid = wgid / nig, fm = gid * WGM, gsz = (nM - fm) < WGM ? (nM - fm) : WGM;
;         u.pm = fm + ((wgid % nig) % gsz); u.pn = (wgid % nig) / gsz; return true;
.LBB0_303:
	s_ashr_i32 s6, s48, 3
	s_add_i32 s6, s50, s6
	s_ashr_i32 s7, s6, 31
	s_lshr_b32 s7, s7, 27
	s_add_i32 s7, s6, s7
	s_ashr_i32 s48, s7, 5
	s_lshl_b32 s48, s48, 3
	s_sub_i32 s49, 0x80, s48
	s_min_i32 s49, s49, 8
	s_andn2_b32 s7, s7, 31
	s_sub_i32 s6, s6, s7
	s_lshr_b32 s69, s6, 3
	s_mul_i32 s7, s69, s49
	s_sub_i32 s6, s6, s7
	s_add_i32 s70, s48, s6

;     __host__ __device__ bool next(int i, Unit& u) const {
;         const long L = (long)i * G + c; if (L >= nwg) return false;
;         int wgid = (int)L; { const int q = nwg / NXCD, r = nwg % NXCD, xcd = wgid % NXCD, off = wgid / NXCD; wgid = (xcd < r ? xcd * (q + 1) : r * (q + 1) + (xcd - r) * q) + off; }
;         const int nig = WGM * nN, gid = wgid / nig, fm = gid * WGM, gsz = (nM - fm) < WGM ? (nM - fm) : WGM;
;         u.pm = fm + ((wgid % nig) % gsz); u.pn = (wgid % nig) / gsz; return true;
.LBB0_411:
	s_add_i32 s68, s68, 1
	s_mul_i32 s4, s68, s56
	s_mul_hi_u32 s5, s68, s57
	s_add_i32 s5, s5, s4
	s_mul_i32 s4, s68, s57
	s_add_u32 s48, s4, s2
	s_addc_u32 s49, s5, s3
	v_cmp_gt_i64_e32 vcc, s[48:49], v[144:145]
	v_cmp_lt_i64_e64 s[4:5], s[48:49], v[142:143]
	s_cbranch_vccnz .LBB0_413
	s_ashr_i32 s18, s48, 31
	s_lshr_b32 s18, s18, 29
	s_add_i32 s18, s48, s18
	s_ashr_i32 s19, s18, 3
	s_and_b32 s18, s18, -8
	s_sub_i32 s18, s48, s18
	s_cmp_lt_i32 s18, 0
	s_cselect_b32 s42, s64, 0x60
	s_mul_i32 s18, s42, s18
	s_add_i32 s18, s18, s19
	s_mul_hi_i32 s19, s18, 0x2aaaaaab
	s_lshr_b32 s42, s19, 31
	s_ashr_i32 s19, s19, 3
	s_add_i32 s19, s19, s42
	s_lshl_b32 s42, s19, 3
	s_sub_i32 s43, 0x80, s42
	s_min_i32 s43, s43, 8
	s_mul_i32 s19, s19, 48
	s_sub_i32 s19, s18, s19
	s_lshr_b32 s18, s19, 3
	s_mul_i32 s43, s18, s43
	s_sub_i32 s19, s19, s43
	s_add_i32 s42, s19, s42

;     __host__ __device__ bool next(int i, Unit& u) const {
;         const long L = (long)i * G + c; if (L >= nwg) return false;
;         int wgid = (int)L; { const int q = nwg / NXCD, r = nwg % NXCD, xcd = wgid % NXCD, off = wgid / NXCD; wgid = (xcd < r ? xcd * (q + 1) : r * (q + 1) + (xcd - r) * q) + off; }
;         const int nig = WGM * nN, gid = wgid / nig, fm = gid * WGM, gsz = (nM - fm) < WGM ? (nM - fm) : WGM;
;         u.pm = fm + ((wgid % nig) % gsz); u.pn = (wgid % nig) / gsz; return true;
.LBB0_622:
	s_ashr_i32 s14, s16, 3
	s_add_i32 s14, s18, s14
	s_ashr_i32 s15, s14, 31
	s_lshr_b32 s15, s15, 28
	s_add_i32 s15, s14, s15
	s_ashr_i32 s16, s15, 4
	s_lshl_b32 s16, s16, 3
	s_sub_i32 s17, 0x80, s16
	s_min_i32 s17, s17, 8
	s_and_b32 s15, s15, -16
	s_sub_i32 s15, s14, s15
	s_lshr_b32 s14, s15, 3
	s_mul_i32 s17, s14, s17
	s_sub_i32 s15, s15, s17
	s_add_i32 s16, s16, s15

;     __host__ __device__ bool next(int i, Unit& u) const {
;         const long L = (long)i * G + c; if (L >= nwg) return false;
;         int wgid = (int)L; { const int q = nwg / NXCD, r = nwg % NXCD, xcd = wgid % NXCD, off = wgid / NXCD; wgid = (xcd < r ? xcd * (q + 1) : r * (q + 1) + (xcd - r) * q) + off; }
;         const int nig = WGM * nN, gid = wgid / nig, fm = gid * WGM, gsz = (nM - fm) < WGM ? (nM - fm) : WGM;
;         u.pm = fm + ((wgid % nig) % gsz); u.pn = (wgid % nig) / gsz; return true;
.LBB0_703:
	s_ashr_i32 s35, s35, 3
	s_add_i32 s35, s47, s35
	s_ashr_i32 s44, s35, 31
	s_lshr_b32 s44, s44, 27
	s_add_i32 s44, s35, s44
	s_ashr_i32 s45, s44, 5
	s_lshl_b32 s45, s45, 3
	s_sub_i32 s46, 0x80, s45
	s_min_i32 s46, s46, 8
	s_andn2_b32 s44, s44, 31
	s_sub_i32 s35, s35, s44
	s_lshr_b32 s44, s35, 3
	s_mul_i32 s46, s44, s46
	s_sub_i32 s35, s35, s46
	s_add_i32 s46, s45, s35

;     __host__ __device__ bool next(int i, Unit& u) const {
;         const long L = (long)i * G + c; if (L >= nwg) return false;
;         int wgid = (int)L; { const int q = nwg / NXCD, r = nwg % NXCD, xcd = wgid % NXCD, off = wgid / NXCD; wgid = (xcd < r ? xcd * (q + 1) : r * (q + 1) + (xcd - r) * q) + off; }
;         const int nig = WGM * nN, gid = wgid / nig, fm = gid * WGM, gsz = (nM - fm) < WGM ? (nM - fm) : WGM;
;         u.pm = fm + ((wgid % nig) % gsz); u.pn = (wgid % nig) / gsz; return true;
.LBB0_807:
	s_add_i32 s57, s57, 1
	s_mul_i32 s4, s57, s33
	s_mul_hi_u32 s5, s57, s46
	s_add_i32 s5, s5, s4
	s_mul_i32 s4, s57, s46
	s_add_u32 s16, s4, s2
	s_addc_u32 s17, s5, s3
	v_cmp_gt_i64_e32 vcc, s[16:17], v[142:143]
	v_cmp_lt_i64_e64 s[4:5], s[16:17], v[140:141]
	s_cbranch_vccnz .LBB0_809
	s_ashr_i32 s12, s16, 31
	s_lshr_b32 s12, s12, 29
	s_add_i32 s12, s16, s12
	s_ashr_i32 s13, s12, 3
	s_and_b32 s12, s12, -8
	s_sub_i32 s12, s16, s12
	s_cmp_lt_i32 s12, 0
	s_cselect_b32 s14, s53, 0x160
	s_mul_i32 s12, s14, s12
	s_add_i32 s12, s12, s13
	s_mul_hi_i32 s13, s12, 0x2e8ba2e9
	s_lshr_b32 s14, s13, 31
	s_ashr_i32 s13, s13, 5
	s_add_i32 s13, s13, s14
	s_lshl_b32 s14, s13, 3
	s_sub_i32 s15, 0x80, s14
	s_min_i32 s15, s15, 8
	s_mulk_i32 s13, 0xb0
	s_sub_i32 s13, s12, s13
	s_lshr_b32 s12, s13, 3
	s_mul_i32 s15, s12, s15
	s_sub_i32 s13, s13, s15
	s_add_i32 s14, s13, s14

;     __host__ __device__ bool next(int i, Unit& u) const {
;         const long L = (long)i * G + c; if (L >= nwg) return false;
;         int wgid = (int)L; { const int q = nwg / NXCD, r = nwg % NXCD, xcd = wgid % NXCD, off = wgid / NXCD; wgid = (xcd < r ? xcd * (q + 1) : r * (q + 1) + (xcd - r) * q) + off; }
;         const int nig = WGM * nN, gid = wgid / nig, fm = gid * WGM, gsz = (nM - fm) < WGM ? (nM - fm) : WGM;
;         u.pm = fm + ((wgid % nig) % gsz); u.pn = (wgid % nig) / gsz; return true;
.LBB0_889:
	s_ashr_i32 s6, s46, 3
	s_add_i32 s6, s48, s6
	s_ashr_i32 s7, s6, 31
	s_lshr_b32 s7, s7, 27
	s_add_i32 s7, s6, s7
	s_ashr_i32 s46, s7, 5
	s_lshl_b32 s46, s46, 3
	s_sub_i32 s47, 0x80, s46
	s_min_i32 s47, s47, 8
	s_andn2_b32 s7, s7, 31
	s_sub_i32 s6, s6, s7
	s_lshr_b32 s66, s6, 3
	s_mul_i32 s7, s66, s47
	s_sub_i32 s6, s6, s7
	s_add_i32 s67, s46, s6

;     __host__ __device__ bool next(int i, Unit& u) const {
;         const long L = (long)i * G + c; if (L >= nwg) return false;
;         int wgid = (int)L; { const int q = nwg / NXCD, r = nwg % NXCD, xcd = wgid % NXCD, off = wgid / NXCD; wgid = (xcd < r ? xcd * (q + 1) : r * (q + 1) + (xcd - r) * q) + off; }
;         const int nig = WGM * nN, gid = wgid / nig, fm = gid * WGM, gsz = (nM - fm) < WGM ? (nM - fm) : WGM;
;         u.pm = fm + ((wgid % nig) % gsz); u.pn = (wgid % nig) / gsz; return true;
.LBB0_1198:
	s_ashr_i32 s1, s1, 3
	s_add_i32 s1, s57, s1
	s_ashr_i32 s54, s1, 31
	s_lshr_b32 s54, s54, 26
	s_add_i32 s54, s1, s54
	s_ashr_i32 s55, s54, 6
	s_lshl_b32 s55, s55, 3
	s_sub_i32 s56, 0x80, s55
	s_min_i32 s56, s56, 8
	s_andn2_b32 s54, s54, 63
	s_sub_i32 s1, s1, s54
	s_lshr_b32 s54, s1, 3
	s_mul_i32 s56, s54, s56
	s_sub_i32 s1, s1, s56
	s_add_i32 s56, s55, s1

;     __host__ __device__ bool next(int i, Unit& u) const {
;         const long L = (long)i * G + c; if (L >= nwg) return false;
;         int wgid = (int)L; { const int q = nwg / NXCD, r = nwg % NXCD, xcd = wgid % NXCD, off = wgid / NXCD; wgid = (xcd < r ? xcd * (q + 1) : r * (q + 1) + (xcd - r) * q) + off; }
;         const int nig = WGM * nN, gid = wgid / nig, fm = gid * WGM, gsz = (nM - fm) < WGM ? (nM - fm) : WGM;
;         u.pm = fm + ((wgid % nig) % gsz); u.pn = (wgid % nig) / gsz; return true;
.LBB0_1444:
	s_ashr_i32 s12, s14, 3
	s_add_i32 s12, s16, s12
	s_ashr_i32 s13, s12, 31
	s_lshr_b32 s13, s13, 22
	s_add_i32 s13, s12, s13
	s_ashr_i32 s14, s13, 10
	s_lshl_b32 s14, s14, 3
	s_sub_i32 s15, 4, s14
	s_min_i32 s15, s15, 8
	s_and_b32 s13, s13, 0xfffffc00
	s_sub_i32 s13, s12, s13
	s_lshr_b32 s12, s13, 2
	s_mul_i32 s15, s12, s15
	s_sub_i32 s13, s13, s15
	s_add_i32 s14, s14, s13

;     __host__ __device__ bool next(int i, Unit& u) const {
;         const long L = (long)i * G + c; if (L >= nwg) return false;
;         int wgid = (int)L; { const int q = nwg / NXCD, r = nwg % NXCD, xcd = wgid % NXCD, off = wgid / NXCD; wgid = (xcd < r ? xcd * (q + 1) : r * (q + 1) + (xcd - r) * q) + off; }
;         const int nig = WGM * nN, gid = wgid / nig, fm = gid * WGM, gsz = (nM - fm) < WGM ? (nM - fm) : WGM;
;         u.pm = fm + ((wgid % nig) % gsz); u.pn = (wgid % nig) / gsz; return true;
.LBB0_1737:
	s_add_i32 s55, s55, 1
	s_mul_i32 s4, s55, s33
	s_mul_hi_u32 s5, s55, s44
	s_add_i32 s5, s5, s4
	s_mul_i32 s4, s55, s44
	s_add_u32 s16, s4, s2
	s_addc_u32 s17, s5, s3
	v_cmp_gt_i64_e32 vcc, s[16:17], v[142:143]
	v_cmp_lt_i64_e64 s[4:5], s[16:17], v[140:141]
	s_cbranch_vccnz .LBB0_1739
	s_ashr_i32 s12, s16, 31
	s_lshr_b32 s12, s12, 29
	s_add_i32 s12, s16, s12
	s_ashr_i32 s13, s12, 3
	s_and_b32 s12, s12, -8
	s_sub_i32 s12, s16, s12
	s_cmp_lt_i32 s12, 0
	s_cselect_b32 s14, s51, 0x160
	s_mul_i32 s12, s14, s12
	s_add_i32 s12, s12, s13
	s_mul_hi_i32 s13, s12, 0x2e8ba2e9
	s_lshr_b32 s14, s13, 31
	s_ashr_i32 s13, s13, 5
	s_add_i32 s13, s13, s14
	s_lshl_b32 s14, s13, 3
	s_sub_i32 s15, 0x80, s14
	s_min_i32 s15, s15, 8
	s_mulk_i32 s13, 0xb0
	s_sub_i32 s13, s12, s13
	s_lshr_b32 s12, s13, 3
	s_mul_i32 s15, s12, s15
	s_sub_i32 s13, s13, s15
	s_add_i32 s14, s13, s14

;     __host__ __device__ bool next(int i, Unit& u) const {
;         const long L = (long)i * G + c; if (L >= nwg) return false;
;         int wgid = (int)L; { const int q = nwg / NXCD, r = nwg % NXCD, xcd = wgid % NXCD, off = wgid / NXCD; wgid = (xcd < r ? xcd * (q + 1) : r * (q + 1) + (xcd - r) * q) + off; }
;         const int nig = WGM * nN, gid = wgid / nig, fm = gid * WGM, gsz = (nM - fm) < WGM ? (nM - fm) : WGM;
;         u.pm = fm + ((wgid % nig) % gsz); u.pn = (wgid % nig) / gsz; return true;
.LBB0_1819:
	s_ashr_i32 s6, s44, 3
	s_add_i32 s6, s46, s6
	s_ashr_i32 s7, s6, 31
	s_lshr_b32 s7, s7, 27
	s_add_i32 s7, s6, s7
	s_ashr_i32 s44, s7, 5
	s_lshl_b32 s44, s44, 3
	s_sub_i32 s45, 0x80, s44
	s_min_i32 s45, s45, 8
	s_andn2_b32 s7, s7, 31
	s_sub_i32 s6, s6, s7
	s_lshr_b32 s64, s6, 3
	s_mul_i32 s7, s64, s45
	s_sub_i32 s6, s6, s7
	s_add_i32 s65, s44, s6
